# final candidate: + DPP butterfly in phase 16 row pass
# speedup vs baseline: 1.0109x; 1.0109x over previous
.LBB0_2681:
	global_load_dwordx4 v[0:3], v[48:49], off offset:1024
	global_load_dwordx4 v[4:7], v[48:49], off offset:2048
	global_load_dwordx4 v[12:15], v[48:49], off offset:3072
	global_load_dwordx4 v[8:11], v[48:49], off
	global_load_dwordx4 v[72:75], v[16:17], off
	global_load_dwordx4 v[76:79], v[18:19], off
	v_add_u32_e32 v148, s2, v148
	v_lshl_add_u64 v[48:49], v[48:49], 0, s[4:5]
	s_waitcnt vmcnt(0)
	global_load_dwordx4 v[170:173], v[20:21], off
	global_load_dwordx4 v[174:177], v[22:23], off
	global_load_dwordx4 v[178:181], v[24:25], off
	global_load_dwordx4 v[182:185], v[26:27], off
	global_load_dwordx4 v[186:189], v[28:29], off
	global_load_dwordx4 v[190:193], v[30:31], off
	global_load_dwordx4 v[194:197], v[32:33], off
	global_load_dwordx4 v[198:201], v[34:35], off
	global_load_dwordx4 v[202:205], v[36:37], off
	global_load_dwordx4 v[206:209], v[38:39], off
	global_load_dwordx4 v[210:213], v[40:41], off
	global_load_dwordx4 v[214:217], v[42:43], off
	global_load_dwordx4 v[218:221], v[44:45], off
	global_load_dwordx4 v[222:225], v[46:47], off
	v_lshlrev_b32_e32 v80, 16, v2
	v_and_b32_e32 v81, 0xffff0000, v2
	v_lshlrev_b32_e32 v52, 16, v12
	v_lshlrev_b32_e32 v85, 16, v8
	v_lshlrev_b32_e32 v84, 16, v10
	v_and_b32_e32 v87, 0xffff0000, v8
	v_and_b32_e32 v86, 0xffff0000, v10
	v_lshlrev_b32_e32 v89, 16, v9
	v_lshlrev_b32_e32 v88, 16, v11
	v_and_b32_e32 v91, 0xffff0000, v9
	v_and_b32_e32 v90, 0xffff0000, v11
	v_and_b32_e32 v53, 0xffff0000, v12
	v_lshlrev_b32_e32 v54, 16, v13
	v_and_b32_e32 v55, 0xffff0000, v13
	v_lshlrev_b32_e32 v11, 16, v1
	v_lshlrev_b32_e32 v10, 16, v0
	v_and_b32_e32 v9, 0xffff0000, v1
	v_and_b32_e32 v8, 0xffff0000, v0
	v_pk_add_f32 v[92:93], v[84:85], v[86:87]
	v_pk_add_f32 v[94:95], v[88:89], v[90:91]
	v_lshlrev_b32_e32 v82, 16, v3
	v_and_b32_e32 v83, 0xffff0000, v3
	v_lshlrev_b32_e32 v2, 16, v14
	v_and_b32_e32 v12, 0xffff0000, v14
	v_pk_add_f32 v[96:97], v[10:11], v[8:9]
	v_add_f32_e32 v3, v52, v53
	v_add_f32_e32 v13, v54, v55
	v_pk_add_f32 v[92:93], v[92:93], v[94:95]
	v_pk_add_f32 v[94:95], v[96:97], v[96:97] op_sel_hi:[0,1]
	v_pk_add_f32 v[100:101], v[2:3], v[12:13]
	v_add_f32_e32 v3, 0, v93
	v_lshlrev_b32_e32 v56, 16, v4
	v_and_b32_e32 v60, 0xffff0000, v4
	v_lshlrev_b32_e32 v58, 16, v5
	v_and_b32_e32 v62, 0xffff0000, v5
	v_add_f32_e32 v57, v80, v81
	v_add_f32_e32 v61, v82, v83
	v_mov_b32_e32 v59, v95
	v_add_f32_e32 v63, v92, v3
	v_lshlrev_b32_e32 v1, 16, v7
	v_lshlrev_b32_e32 v0, 16, v6
	v_and_b32_e32 v7, 0xffff0000, v7
	v_and_b32_e32 v6, 0xffff0000, v6
	v_pk_add_f32 v[96:97], v[56:57], v[60:61]
	v_pk_add_f32 v[92:93], v[58:59], v[62:63]
	v_pk_add_f32 v[98:99], v[0:1], v[6:7]
	v_pk_add_f32 v[92:93], v[96:97], v[92:93]
	v_pk_add_f32 v[98:99], v[98:99], v[98:99] op_sel_hi:[0,1]
	v_pk_add_f32 v[92:93], v[92:93], v[92:93] op_sel_hi:[0,1]
	v_lshlrev_b32_e32 v4, 16, v15
	v_and_b32_e32 v14, 0xffff0000, v15
	v_mov_b32_e32 v5, v99
	v_mov_b32_e32 v15, v93
	v_pk_add_f32 v[92:93], v[4:5], v[14:15]
	s_nop 0
	v_pk_add_f32 v[92:93], v[100:101], v[92:93]
	s_nop 0
	v_add_f32_e32 v3, v92, v93
	s_nop 1
	v_add_f32_dpp v3, v3, v3 quad_perm:[1,0,3,2] row_mask:0xf bank_mask:0xf
	s_nop 1
	v_add_f32_dpp v3, v3, v3 quad_perm:[2,3,0,1] row_mask:0xf bank_mask:0xf
	s_nop 1
	v_add_f32_dpp v3, v3, v3 row_half_mirror row_mask:0xf bank_mask:0xf
	s_nop 1
	v_add_f32_dpp v3, v3, v3 row_mirror row_mask:0xf bank_mask:0xf
	s_nop 1
	v_add_f32_dpp v3, v3, v3 row_bcast:15 row_mask:0xa bank_mask:0xf
	s_nop 0
	v_readlane_b32 s86, v3, 31
	v_readlane_b32 s87, v3, 63
	s_nop 1
	v_mov_b32_e32 v3, s86
	v_add_f32_e32 v3, s87, v3
	v_fmac_f32_e32 v91, 0xba000000, v3
	v_fmac_f32_e32 v87, 0xba000000, v3
	v_fmac_f32_e32 v90, 0xba000000, v3
	v_fmac_f32_e32 v86, 0xba000000, v3
	v_fmac_f32_e32 v8, 0xba000000, v3
	v_fmac_f32_e32 v9, 0xba000000, v3
	v_fmac_f32_e32 v11, 0xba000000, v3
	v_fmac_f32_e32 v89, 0xba000000, v3
	v_fmac_f32_e32 v85, 0xba000000, v3
	v_fmac_f32_e32 v88, 0xba000000, v3
	v_fmac_f32_e32 v84, 0xba000000, v3
	v_fmac_f32_e32 v10, 0xba000000, v3
	v_mov_b32_e32 v96, v87
	v_mov_b32_e32 v97, v86
	v_mov_b32_e32 v102, v91
	v_mov_b32_e32 v103, v90
	v_mov_b32_e32 v104, v11
	v_mov_b32_e32 v105, v9
	v_mov_b32_e32 v11, v8
	v_mov_b32_e32 v94, v85
	v_mov_b32_e32 v95, v84
	v_mov_b32_e32 v100, v89
	v_mov_b32_e32 v101, v88
	v_pk_mul_f32 v[96:97], v[96:97], v[96:97]
	v_pk_mul_f32 v[102:103], v[102:103], v[102:103]
	v_pk_mul_f32 v[112:113], v[104:105], v[104:105]
	v_pk_mul_f32 v[114:115], v[10:11], v[10:11]
	v_fmac_f32_e32 v80, 0xba000000, v3
	v_fmac_f32_e32 v82, 0xba000000, v3
	v_pk_fma_f32 v[94:95], v[94:95], v[94:95], v[96:97]
	v_pk_fma_f32 v[96:97], v[100:101], v[100:101], v[102:103]
	v_pk_mov_b32 v[100:101], v[114:115], v[112:113] op_sel:[1,0]
	v_mov_b32_e32 v115, v113
	v_fmac_f32_e32 v81, 0xba000000, v3
	v_fmac_f32_e32 v83, 0xba000000, v3
	v_fmac_f32_e32 v6, 0xba000000, v3
	v_fmac_f32_e32 v7, 0xba000000, v3
	v_fmac_f32_e32 v1, 0xba000000, v3
	v_mul_f32_e32 v8, v80, v80
	v_mul_f32_e32 v106, v82, v82
	v_pk_add_f32 v[94:95], v[94:95], v[96:97]
	v_pk_add_f32 v[96:97], v[100:101], v[114:115]
	v_fmac_f32_e32 v62, 0xba000000, v3
	v_fmac_f32_e32 v58, 0xba000000, v3
	v_fmac_f32_e32 v60, 0xba000000, v3
	v_fmac_f32_e32 v56, 0xba000000, v3
	v_fmac_f32_e32 v0, 0xba000000, v3
	v_mov_b32_e32 v108, v1
	v_mov_b32_e32 v109, v7
	v_mov_b32_e32 v1, v6
	v_pk_fma_f32 v[8:9], v[80:81], v[80:81], v[8:9] op_sel_hi:[1,1,0]
	v_pk_fma_f32 v[106:107], v[82:83], v[82:83], v[106:107] op_sel_hi:[1,1,0]
	v_pk_add_f32 v[94:95], v[94:95], v[94:95] op_sel_hi:[0,1]
	v_pk_add_f32 v[96:97], v[96:97], v[96:97] op_sel_hi:[0,1]
	v_pk_mul_f32 v[116:117], v[108:109], v[108:109]
	v_pk_mul_f32 v[118:119], v[0:1], v[0:1]
	v_mul_f32_e32 v8, v56, v56
	v_mul_f32_e32 v106, v60, v60
	v_mul_f32_e32 v96, v58, v58
	v_mul_f32_e32 v94, v62, v62
	v_fmac_f32_e32 v52, 0xba000000, v3
	v_fmac_f32_e32 v54, 0xba000000, v3
	v_pk_mov_b32 v[102:103], v[118:119], v[116:117] op_sel:[1,0]
	v_mov_b32_e32 v119, v117
	v_pk_add_f32 v[8:9], v[8:9], v[106:107]
	v_pk_add_f32 v[94:95], v[96:97], v[94:95]
	v_fmac_f32_e32 v53, 0xba000000, v3
	v_fmac_f32_e32 v55, 0xba000000, v3
	v_mul_f32_e32 v6, v52, v52
	v_mul_f32_e32 v110, v54, v54
	v_pk_add_f32 v[100:101], v[102:103], v[118:119]
	v_pk_add_f32 v[8:9], v[8:9], v[94:95]
	v_fmac_f32_e32 v14, 0xba000000, v3
	v_fmac_f32_e32 v4, 0xba000000, v3
	v_fmac_f32_e32 v12, 0xba000000, v3
	v_fmac_f32_e32 v2, 0xba000000, v3
	v_pk_fma_f32 v[6:7], v[52:53], v[52:53], v[6:7] op_sel_hi:[1,1,0]
	v_pk_fma_f32 v[110:111], v[54:55], v[54:55], v[110:111] op_sel_hi:[1,1,0]
	v_pk_add_f32 v[100:101], v[100:101], v[100:101] op_sel_hi:[0,1]
	v_pk_add_f32 v[8:9], v[8:9], v[8:9] op_sel_hi:[0,1]
	v_mul_f32_e32 v6, v2, v2
	v_mul_f32_e32 v110, v12, v12
	v_mul_f32_e32 v100, v4, v4
	v_mul_f32_e32 v8, v14, v14
	v_pk_add_f32 v[6:7], v[6:7], v[110:111]
	v_pk_add_f32 v[8:9], v[100:101], v[8:9]
	v_mov_b32_e32 v92, v85
	v_pk_add_f32 v[6:7], v[6:7], v[8:9]
	v_mov_b32_e32 v93, v87
	v_add_f32_e32 v3, v6, v7
	v_mov_b32_e32 v98, v89
	v_mov_b32_e32 v99, v91
	v_mov_b32_e32 v85, v86
	v_mov_b32_e32 v89, v90
	v_mov_b32_e32 v59, v62
	v_mov_b32_e32 v57, v60
	s_nop 1
	v_add_f32_dpp v3, v3, v3 quad_perm:[1,0,3,2] row_mask:0xf bank_mask:0xf
	s_nop 1
	v_add_f32_dpp v3, v3, v3 quad_perm:[2,3,0,1] row_mask:0xf bank_mask:0xf
	s_nop 1
	v_add_f32_dpp v3, v3, v3 row_half_mirror row_mask:0xf bank_mask:0xf
	s_nop 1
	v_add_f32_dpp v3, v3, v3 row_mirror row_mask:0xf bank_mask:0xf
	s_nop 1
	v_add_f32_dpp v3, v3, v3 row_bcast:15 row_mask:0xa bank_mask:0xf
	s_nop 0
	v_readlane_b32 s86, v3, 31
	v_readlane_b32 s87, v3, 63
	s_nop 1
	v_mov_b32_e32 v3, s86
	v_add_f32_e32 v3, s87, v3
	v_fmamk_f32 v3, v3, 0x3a000000, v70
	v_mul_f32_e32 v5, 0x4f800000, v3
	v_cmp_gt_f32_e32 vcc, s3, v3
	s_nop 1
	v_cndmask_b32_e32 v3, v3, v5, vcc
	v_sqrt_f32_e32 v5, v3
	s_nop 0
	v_add_u32_e32 v6, -1, v5
	v_add_u32_e32 v7, 1, v5
	v_fma_f32 v8, -v6, v5, v3
	v_fma_f32 v9, -v7, v5, v3
	v_cmp_ge_f32_e64 s[0:1], 0, v8
	s_nop 1
	v_cndmask_b32_e64 v5, v5, v6, s[0:1]
	v_cmp_lt_f32_e64 s[0:1], 0, v9
	s_nop 1
	v_cndmask_b32_e64 v5, v5, v7, s[0:1]
	v_mul_f32_e32 v6, 0x37800000, v5
	v_cndmask_b32_e32 v5, v5, v6, vcc
	v_cmp_class_f32_e32 vcc, v3, v71
	s_nop 1
	v_cndmask_b32_e32 v3, v5, v3, vcc
	v_div_scale_f32 v5, s[0:1], v3, v3, 1.0
	v_rcp_f32_e32 v7, v5
	v_div_scale_f32 v6, vcc, 1.0, v3, 1.0
	v_fma_f32 v8, -v5, v7, 1.0
	v_fmac_f32_e32 v7, v8, v7
	v_mul_f32_e32 v8, v6, v7
	v_fma_f32 v9, -v5, v8, v6
	v_fmac_f32_e32 v8, v9, v7
	v_fma_f32 v5, -v5, v8, v6
	v_div_fmas_f32 v5, v5, v7, v8
	v_div_fixup_f32 v94, v5, v3, 1.0
	v_pk_mul_f32 v[6:7], v[92:93], v[94:95] op_sel_hi:[1,0]
	v_pk_mul_f32 v[8:9], v[98:99], v[94:95] op_sel_hi:[1,0]
	v_pk_fma_f32 v[6:7], v[72:73], v[6:7], v[76:77]
	v_pk_fma_f32 v[8:9], v[74:75], v[8:9], v[78:79]
	global_store_dwordx4 v[50:51], v[6:9], off offset:-4096
	s_nop 0
	v_pk_mul_f32 v[76:77], v[88:89], v[94:95] op_sel_hi:[1,0]
	v_pk_mul_f32 v[78:79], v[84:85], v[94:95] op_sel_hi:[1,0]
	v_pk_mul_f32 v[10:11], v[10:11], v[94:95] op_sel_hi:[1,0]
	v_pk_mul_f32 v[56:57], v[56:57], v[94:95] op_sel_hi:[1,0]
	v_pk_mul_f32 v[0:1], v[0:1], v[94:95] op_sel_hi:[1,0]
	v_mov_b32_e32 v5, v14
	v_mov_b32_e32 v3, v12
	v_pk_mul_f32 v[4:5], v[4:5], v[94:95] op_sel_hi:[1,0]
	v_cmp_lt_i32_e32 vcc, s10, v148
	s_or_b64 s[8:9], vcc, s[8:9]
	s_waitcnt vmcnt(13)
	v_pk_fma_f32 v[6:7], v[170:171], v[78:79], v[174:175]
	v_pk_fma_f32 v[8:9], v[172:173], v[76:77], v[176:177]
	global_store_dwordx4 v[50:51], v[6:9], off offset:-4080
	s_nop 0
	v_pk_mul_f32 v[76:77], v[104:105], v[94:95] op_sel_hi:[1,0]
	s_waitcnt vmcnt(12)
	v_pk_fma_f32 v[6:7], v[178:179], v[10:11], v[182:183]
	v_pk_fma_f32 v[8:9], v[180:181], v[76:77], v[184:185]
	global_store_dwordx4 v[50:51], v[6:9], off offset:-2048
	s_nop 0
	v_pk_mul_f32 v[10:11], v[82:83], v[94:95] op_sel_hi:[1,0]
	v_pk_mul_f32 v[76:77], v[80:81], v[94:95] op_sel_hi:[1,0]
	s_waitcnt vmcnt(11)
	v_pk_fma_f32 v[8:9], v[188:189], v[10:11], v[192:193]
	v_pk_fma_f32 v[6:7], v[186:187], v[76:77], v[190:191]
	global_store_dwordx4 v[50:51], v[6:9], off offset:-2032
	s_nop 0
	v_pk_mul_f32 v[10:11], v[58:59], v[94:95] op_sel_hi:[1,0]
	s_waitcnt vmcnt(10)
	v_pk_fma_f32 v[6:7], v[194:195], v[56:57], v[198:199]
	v_pk_fma_f32 v[8:9], v[196:197], v[10:11], v[200:201]
	global_store_dwordx4 v[50:51], v[6:9], off
	s_nop 0
	v_pk_mul_f32 v[10:11], v[108:109], v[94:95] op_sel_hi:[1,0]
	s_waitcnt vmcnt(9)
	v_pk_fma_f32 v[6:7], v[202:203], v[0:1], v[206:207]
	v_pk_fma_f32 v[8:9], v[204:205], v[10:11], v[208:209]
	global_store_dwordx4 v[50:51], v[6:9], off offset:16
	s_nop 0
	v_pk_mul_f32 v[0:1], v[54:55], v[94:95] op_sel_hi:[1,0]
	v_pk_mul_f32 v[10:11], v[52:53], v[94:95] op_sel_hi:[1,0]
	s_waitcnt vmcnt(8)
	v_pk_fma_f32 v[8:9], v[212:213], v[0:1], v[216:217]
	v_pk_fma_f32 v[6:7], v[210:211], v[10:11], v[214:215]
	global_store_dwordx4 v[50:51], v[6:9], off offset:2048
	s_nop 0
	v_pk_mul_f32 v[0:1], v[2:3], v[94:95] op_sel_hi:[1,0]
	s_waitcnt vmcnt(7)
	v_pk_fma_f32 v[2:3], v[220:221], v[4:5], v[224:225]
	v_pk_fma_f32 v[0:1], v[218:219], v[0:1], v[222:223]
	global_store_dwordx4 v[50:51], v[0:3], off offset:2064
	v_lshl_add_u64 v[50:51], v[50:51], 0, s[6:7]
	s_andn2_b64 exec, exec, s[8:9]
	s_cbranch_execnz .LBB0_2681
